# ret_out diagonal block: its four LDS reads issued together (counted waits)
# baseline (speedup 1.0000x reference)
; DI unsigned pk2(float lo, float hi) { unsigned r; asm volatile("v_cvt_pk_bf16_f32 %0, %1, %2" : "=v"(r) : "v"(lo), "v"(hi)); return r; }
; DI f32x4 mmaT(bf16x8 a_m, bf16x8 b_n, f32x4 c) { return __builtin_amdgcn_mfma_f32_16x16x32_bf16(b_n, a_m, c, 0, 0, 0); }
; DI void ret_out_unit(const Params& p, int hf, int bl, int c, int hd, unsigned char* shm, int tid, bool dry = false) {
;     ...
;     for (int n = 0; n < 8; ++n) {
;       if (n <= (wid | 1)) {
;         uint2 w; w.x = 0u; w.y = 0u;
;         if (n <= wid) {
;           f32x4 s = (f32x4){0.f, 0.f, 0.f, 0.f};
; #pragma unroll
;           for (int ks = 0; ks < 4; ++ks) s = mmaT(aq[ks], ldf(sK, LD, 16 * n, 32 * ks, fr, fq), s);
;           float r[4];
; #pragma unroll
;           for (int j = 0; j < 4; ++j) { const int d = i_row - (16 * n + 4 * fq + j); r[j] = (d >= 0) ? s[j] * __expf(lg * (float)d) : 0.f; }
;           w.x = pk2(r[0], r[1]); w.y = pk2(r[2], r[3]);
;         }
;         *(uint2*)(sS + i_row * LD + 16 * n + 4 * fq) = w;
.LBB0_460:
	v_cmp_lt_i32_e32 vcc, 6, v73
	v_mov_b32_e32 v32, 0
	v_mov_b32_e32 v33, 0
	s_and_saveexec_b64 s[4:5], vcc
	s_cbranch_execz .LBB0_462
	v_mad_u32_u24 v38, v74, s66, v38
	ds_read_b128 v[240:243], v38 offset:65280
	ds_read_b128 v[244:247], v38 offset:65344
	ds_read_b128 v[248:251], v38 offset:65408
	ds_read_b128 v[172:175], v38 offset:65472
	s_nop 4
	s_nop 2
	s_waitcnt lgkmcnt(3)
	v_mfma_f32_16x16x32_bf16 v[28:31], v[240:243], v[28:31], 0
	s_waitcnt lgkmcnt(2)
	v_mfma_f32_16x16x32_bf16 v[24:27], v[244:247], v[24:27], v[28:31]
	s_waitcnt lgkmcnt(1)
	v_mfma_f32_16x16x32_bf16 v[20:23], v[248:251], v[20:23], v[24:27]
	s_waitcnt lgkmcnt(0)
	v_mfma_f32_16x16x32_bf16 v[16:19], v[172:175], v[16:19], v[20:23]
	s_nop 2
	v_or_b32_e32 v20, 0x70, v36
	v_sub_u32_e32 v20, v68, v20
	v_cmp_lt_i32_e32 vcc, -1, v20
	v_cvt_f32_u32_e32 v20, v20
	v_mul_f32_e32 v20, v69, v20
	v_mul_f32_e32 v20, 0x3fb8aa3b, v20
	v_exp_f32_e32 v20, v20
	s_nop 0
	v_mul_f32_e32 v16, v20, v16
	v_or_b32_e32 v20, 0x71, v36
	v_sub_u32_e32 v20, v68, v20
	v_cndmask_b32_e32 v16, 0, v16, vcc
	v_cmp_lt_i32_e32 vcc, -1, v20
	v_cvt_f32_u32_e32 v20, v20
	v_mul_f32_e32 v20, v69, v20
	v_mul_f32_e32 v20, 0x3fb8aa3b, v20
	v_exp_f32_e32 v20, v20
	s_nop 0
	v_mul_f32_e32 v17, v20, v17
	v_or_b32_e32 v20, 0x72, v36
	v_sub_u32_e32 v20, v68, v20
	v_cndmask_b32_e32 v17, 0, v17, vcc
	v_cmp_lt_i32_e32 vcc, -1, v20
	v_cvt_f32_u32_e32 v20, v20
	v_cvt_pk_bf16_f32 v32, v16, v17
	v_mul_f32_e32 v20, v69, v20
	v_mul_f32_e32 v20, 0x3fb8aa3b, v20
	v_exp_f32_e32 v20, v20
	s_nop 0
	v_mul_f32_e32 v18, v20, v18
	v_or_b32_e32 v20, 0x73, v36
	v_sub_u32_e32 v20, v68, v20
	v_cndmask_b32_e32 v18, 0, v18, vcc
	v_cmp_lt_i32_e32 vcc, -1, v20
	v_cvt_f32_u32_e32 v20, v20
	v_mul_f32_e32 v20, v69, v20
	v_mul_f32_e32 v20, 0x3fb8aa3b, v20
	v_exp_f32_e32 v20, v20
	s_nop 0
	v_mul_f32_e32 v19, v20, v19
	v_cndmask_b32_e32 v19, 0, v19, vcc
	v_cvt_pk_bf16_f32 v33, v18, v19
